# v34: GLA in-projection scheduled as 12 column tiles (the 13th held only the 16 gk_low columns + padding); gk_low computed by a small direct 16x16x32 bf16 MFMA pass per workgroup
# speedup vs baseline: 1.0083x; 1.0014x over previous
.LBB0_49:
	s_mov_b32 s32, s24
	s_cmp_eq_u32 s24, 0xd00
	s_cselect_b32 s24, 0xc00, s24
	s_lshr_b32 s25, s24, 5
	v_cvt_f32_u32_e32 v12, s25
	s_lshr_b32 s18, s24, 1
	v_readlane_b32 s2, v247, 0
	v_mov_b32_e32 v13, v195
	s_cmp_lt_i32 s2, s18
	s_cselect_b64 s[30:31], -1, 0
	s_cmp_ge_i32 s2, s18
	v_readfirstlane_b32 s2, v13
	s_cbranch_scc1 .LBB0_51
	v_rcp_iflag_f32_e32 v0, v12
	s_lshr_b32 s5, s24, 4
	v_readlane_b32 s19, v246, 50
	s_or_b32 s5, s5, s19
	v_mul_f32_e32 v0, 0x4f7ffffe, v0
	v_cvt_u32_f32_e32 v0, v0
	v_readlane_b32 s19, v246, 49
	s_sub_i32 s27, 0, s25
	s_mul_i32 s5, s5, s19
	v_readfirstlane_b32 s28, v0
	v_readlane_b32 s19, v247, 24
	s_mul_i32 s27, s27, s28
	s_add_i32 s5, s5, s19
	s_mul_hi_u32 s27, s28, s27
	s_abs_i32 s26, s5
	s_add_i32 s28, s28, s27
	s_mul_hi_u32 s27, s26, s28
	s_mul_i32 s28, s27, s25
	s_sub_i32 s26, s26, s28
	s_ashr_i32 s19, s5, 31
	s_add_i32 s28, s27, 1
	s_sub_i32 s33, s26, s25
	s_cmp_ge_u32 s26, s25
	s_cselect_b32 s27, s28, s27
	s_cselect_b32 s26, s33, s26
	s_add_i32 s28, s27, 1
	s_cmp_ge_u32 s26, s25
	s_cselect_b32 s26, s28, s27
	s_xor_b32 s26, s26, s19
	s_sub_i32 s19, s26, s19
	s_lshl_b32 s28, s19, 3
	s_sub_i32 s26, 0x80, s28
	s_min_i32 s33, s26, 8
	s_sext_i32_i16 s26, s33
	v_cvt_f32_i32_e32 v0, s26
	s_mul_i32 s19, s19, s25
	s_sub_i32 s5, s5, s19
	s_sext_i32_i16 s19, s5
	s_waitcnt lgkmcnt(0)
	v_cvt_f32_i32_e32 v1, s19
	v_rcp_iflag_f32_e32 v2, v0
	s_xor_b32 s19, s19, s26
	s_ashr_i32 s19, s19, 30
	s_or_b32 s19, s19, 1
	v_mul_f32_e32 v2, v1, v2
	v_trunc_f32_e32 v2, v2
	v_fma_f32 v1, -v2, v0, v1
	v_cvt_i32_f32_e32 v2, v2
	v_cmp_ge_f32_e64 s[26:27], |v1|, |v0|
	s_and_b64 s[26:27], s[26:27], exec
	s_cselect_b32 s19, s19, 0
	v_readfirstlane_b32 s26, v2
	s_add_i32 s19, s26, s19
	s_sext_i32_i16 s26, s19
	s_mul_i32 s19, s19, s33
	s_sub_i32 s5, s5, s19
	s_sext_i32_i16 s5, s5
	v_readlane_b32 s33, v245, 29
	s_add_i32 s68, s28, s5
.LBB0_51:
	s_andn2_b64 vcc, exec, s[30:31]
	s_cbranch_vccnz .LBB0_123
	s_cmp_lg_u32 s32, 0xd00
	s_cbranch_scc1 .Lmy_gk_skip
	v_readlane_b32 s100, v247, 0
	v_lshrrev_b32_e32 v0, 6, v13
	v_and_b32_e32 v1, 15, v13
	v_bfe_u32 v2, v13, 4, 2
	s_lshl_b32 s100, s100, 7
	v_lshl_add_u32 v3, v0, 4, v1
	v_add_u32_e32 v3, s100, v3
	v_lshlrev_b32_e32 v4, 11, v3
	v_lshl_add_u32 v4, v2, 4, v4
	v_add_u32_e32 v5, 0xc00, v1
	v_lshlrev_b32_e32 v5, 11, v5
	v_lshl_add_u32 v5, v2, 4, v5
	v_lshlrev_b32_e32 v6, 6, v3
	global_load_dwordx4 v[112:115], v6, s[14:15]
	global_load_dwordx4 v[116:119], v6, s[14:15] offset:16
	global_load_dwordx4 v[120:123], v6, s[14:15] offset:32
	global_load_dwordx4 v[124:127], v6, s[14:15] offset:48
	global_load_dwordx4 v[16:19], v5, s[6:7]
	global_load_dwordx4 v[32:35], v4, s[12:13]
	global_load_dwordx4 v[20:23], v5, s[6:7] offset:64
	global_load_dwordx4 v[36:39], v4, s[12:13] offset:64
	global_load_dwordx4 v[24:27], v5, s[6:7] offset:128
	global_load_dwordx4 v[40:43], v4, s[12:13] offset:128
	global_load_dwordx4 v[28:31], v5, s[6:7] offset:192
	global_load_dwordx4 v[44:47], v4, s[12:13] offset:192
	global_load_dwordx4 v[48:51], v5, s[6:7] offset:256
	global_load_dwordx4 v[64:67], v4, s[12:13] offset:256
	global_load_dwordx4 v[52:55], v5, s[6:7] offset:320
	global_load_dwordx4 v[68:71], v4, s[12:13] offset:320
	global_load_dwordx4 v[56:59], v5, s[6:7] offset:384
	global_load_dwordx4 v[72:75], v4, s[12:13] offset:384
	global_load_dwordx4 v[60:63], v5, s[6:7] offset:448
	global_load_dwordx4 v[76:79], v4, s[12:13] offset:448
	global_load_dwordx4 v[80:83], v5, s[6:7] offset:512
	global_load_dwordx4 v[96:99], v4, s[12:13] offset:512
	global_load_dwordx4 v[84:87], v5, s[6:7] offset:576
	global_load_dwordx4 v[100:103], v4, s[12:13] offset:576
	global_load_dwordx4 v[88:91], v5, s[6:7] offset:640
	global_load_dwordx4 v[104:107], v4, s[12:13] offset:640
	global_load_dwordx4 v[92:95], v5, s[6:7] offset:704
	global_load_dwordx4 v[108:111], v4, s[12:13] offset:704
	v_mov_b32_e32 v8, 0
	v_mov_b32_e32 v9, 0
	v_mov_b32_e32 v10, 0
	v_mov_b32_e32 v11, 0
	s_waitcnt vmcnt(16)
	v_mfma_f32_16x16x32_bf16 v[8:11], v[16:19], v[32:35], v[8:11]
	v_mfma_f32_16x16x32_bf16 v[8:11], v[20:23], v[36:39], v[8:11]
	v_mfma_f32_16x16x32_bf16 v[8:11], v[24:27], v[40:43], v[8:11]
	v_mfma_f32_16x16x32_bf16 v[8:11], v[28:31], v[44:47], v[8:11]
	global_load_dwordx4 v[16:19], v5, s[6:7] offset:768
	global_load_dwordx4 v[32:35], v4, s[12:13] offset:768
	global_load_dwordx4 v[20:23], v5, s[6:7] offset:832
	global_load_dwordx4 v[36:39], v4, s[12:13] offset:832
	global_load_dwordx4 v[24:27], v5, s[6:7] offset:896
	global_load_dwordx4 v[40:43], v4, s[12:13] offset:896
	global_load_dwordx4 v[28:31], v5, s[6:7] offset:960
	global_load_dwordx4 v[44:47], v4, s[12:13] offset:960
	s_waitcnt vmcnt(16)
	v_mfma_f32_16x16x32_bf16 v[8:11], v[48:51], v[64:67], v[8:11]
	v_mfma_f32_16x16x32_bf16 v[8:11], v[52:55], v[68:71], v[8:11]
	v_mfma_f32_16x16x32_bf16 v[8:11], v[56:59], v[72:75], v[8:11]
	v_mfma_f32_16x16x32_bf16 v[8:11], v[60:63], v[76:79], v[8:11]
	global_load_dwordx4 v[48:51], v5, s[6:7] offset:1024
	global_load_dwordx4 v[64:67], v4, s[12:13] offset:1024
	global_load_dwordx4 v[52:55], v5, s[6:7] offset:1088
	global_load_dwordx4 v[68:71], v4, s[12:13] offset:1088
	global_load_dwordx4 v[56:59], v5, s[6:7] offset:1152
	global_load_dwordx4 v[72:75], v4, s[12:13] offset:1152
	global_load_dwordx4 v[60:63], v5, s[6:7] offset:1216
	global_load_dwordx4 v[76:79], v4, s[12:13] offset:1216
	s_waitcnt vmcnt(16)
	v_mfma_f32_16x16x32_bf16 v[8:11], v[80:83], v[96:99], v[8:11]
	v_mfma_f32_16x16x32_bf16 v[8:11], v[84:87], v[100:103], v[8:11]
	v_mfma_f32_16x16x32_bf16 v[8:11], v[88:91], v[104:107], v[8:11]
	v_mfma_f32_16x16x32_bf16 v[8:11], v[92:95], v[108:111], v[8:11]
	global_load_dwordx4 v[80:83], v5, s[6:7] offset:1280
	global_load_dwordx4 v[96:99], v4, s[12:13] offset:1280
	global_load_dwordx4 v[84:87], v5, s[6:7] offset:1344
	global_load_dwordx4 v[100:103], v4, s[12:13] offset:1344
	global_load_dwordx4 v[88:91], v5, s[6:7] offset:1408
	global_load_dwordx4 v[104:107], v4, s[12:13] offset:1408
	global_load_dwordx4 v[92:95], v5, s[6:7] offset:1472
	global_load_dwordx4 v[108:111], v4, s[12:13] offset:1472
	s_waitcnt vmcnt(16)
	v_mfma_f32_16x16x32_bf16 v[8:11], v[16:19], v[32:35], v[8:11]
	v_mfma_f32_16x16x32_bf16 v[8:11], v[20:23], v[36:39], v[8:11]
	v_mfma_f32_16x16x32_bf16 v[8:11], v[24:27], v[40:43], v[8:11]
	v_mfma_f32_16x16x32_bf16 v[8:11], v[28:31], v[44:47], v[8:11]
	global_load_dwordx4 v[16:19], v5, s[6:7] offset:1536
	global_load_dwordx4 v[32:35], v4, s[12:13] offset:1536
	global_load_dwordx4 v[20:23], v5, s[6:7] offset:1600
	global_load_dwordx4 v[36:39], v4, s[12:13] offset:1600
	global_load_dwordx4 v[24:27], v5, s[6:7] offset:1664
	global_load_dwordx4 v[40:43], v4, s[12:13] offset:1664
	global_load_dwordx4 v[28:31], v5, s[6:7] offset:1728
	global_load_dwordx4 v[44:47], v4, s[12:13] offset:1728
	s_waitcnt vmcnt(16)
	v_mfma_f32_16x16x32_bf16 v[8:11], v[48:51], v[64:67], v[8:11]
	v_mfma_f32_16x16x32_bf16 v[8:11], v[52:55], v[68:71], v[8:11]
	v_mfma_f32_16x16x32_bf16 v[8:11], v[56:59], v[72:75], v[8:11]
	v_mfma_f32_16x16x32_bf16 v[8:11], v[60:63], v[76:79], v[8:11]
	global_load_dwordx4 v[48:51], v5, s[6:7] offset:1792
	global_load_dwordx4 v[64:67], v4, s[12:13] offset:1792
	global_load_dwordx4 v[52:55], v5, s[6:7] offset:1856
	global_load_dwordx4 v[68:71], v4, s[12:13] offset:1856
	global_load_dwordx4 v[56:59], v5, s[6:7] offset:1920
	global_load_dwordx4 v[72:75], v4, s[12:13] offset:1920
	global_load_dwordx4 v[60:63], v5, s[6:7] offset:1984
	global_load_dwordx4 v[76:79], v4, s[12:13] offset:1984
	s_waitcnt vmcnt(16)
	v_mfma_f32_16x16x32_bf16 v[8:11], v[80:83], v[96:99], v[8:11]
	v_mfma_f32_16x16x32_bf16 v[8:11], v[84:87], v[100:103], v[8:11]
	v_mfma_f32_16x16x32_bf16 v[8:11], v[88:91], v[104:107], v[8:11]
	v_mfma_f32_16x16x32_bf16 v[8:11], v[92:95], v[108:111], v[8:11]
	s_waitcnt vmcnt(8)
	v_mfma_f32_16x16x32_bf16 v[8:11], v[16:19], v[32:35], v[8:11]
	v_mfma_f32_16x16x32_bf16 v[8:11], v[20:23], v[36:39], v[8:11]
	v_mfma_f32_16x16x32_bf16 v[8:11], v[24:27], v[40:43], v[8:11]
	v_mfma_f32_16x16x32_bf16 v[8:11], v[28:31], v[44:47], v[8:11]
	s_waitcnt vmcnt(0)
	v_mfma_f32_16x16x32_bf16 v[8:11], v[48:51], v[64:67], v[8:11]
	v_mfma_f32_16x16x32_bf16 v[8:11], v[52:55], v[68:71], v[8:11]
	v_mfma_f32_16x16x32_bf16 v[8:11], v[56:59], v[72:75], v[8:11]
	v_mfma_f32_16x16x32_bf16 v[8:11], v[60:63], v[76:79], v[8:11]
	v_add_f32_e32 v112, v112, v113
	v_add_f32_e32 v114, v114, v115
	v_add_f32_e32 v112, v112, v114
	v_add_f32_e32 v116, v116, v117
	v_add_f32_e32 v118, v118, v119
	v_add_f32_e32 v116, v116, v118
	v_add_f32_e32 v120, v120, v121
	v_add_f32_e32 v122, v122, v123
	v_add_f32_e32 v120, v120, v122
	v_add_f32_e32 v124, v124, v125
	v_add_f32_e32 v126, v126, v127
	v_add_f32_e32 v124, v124, v126
	v_add_f32_e32 v112, v112, v116
	v_add_f32_e32 v120, v120, v124
	v_add_f32_e32 v112, v112, v120
	v_fmamk_f32 v112, v112, 0x3a800000, v194
	v_rsq_f32_e32 v112, v112
	v_mul_u32_u24_e32 v6, 0x1a00, v3
	v_lshl_add_u32 v6, v2, 3, v6
	v_add_u32_e32 v6, 0x1800, v6
	s_nop 7
	v_mul_f32_e32 v8, v8, v112
	v_mul_f32_e32 v9, v9, v112
	v_mul_f32_e32 v10, v10, v112
	v_mul_f32_e32 v11, v11, v112
	v_cvt_pk_bf16_f32 v8, v8, v9
	v_cvt_pk_bf16_f32 v9, v10, v11
	global_store_dwordx2 v6, v[8:9], s[16:17]
.Lmy_gk_skip:
	s_cmp_eq_u64 s[14:15], 0
	s_cbranch_scc1 .Lmy_ssq_skip
	v_and_b32_e32 v128, 63, v13
	v_lshlrev_b32_e32 v128, 4, v128
	s_lshl_b32 s33, s2, 5
	s_lshl_b32 s46, s68, 14
	s_add_u32 s46, s14, s46
	s_addc_u32 s47, s15, 0
	s_add_u32 s46, s46, s33
	s_addc_u32 s47, s47, 0
	s_lshl_b32 m0, s68, 11
	s_and_b32 m0, m0, 0x4000
	s_add_i32 m0, m0, s33
	s_add_i32 m0, m0, 0x20000
	s_nop 0
	global_load_lds_dwordx4 v128, s[46:47]
	global_load_lds_dwordx4 v128, s[46:47] offset:1024
	s_cmp_lt_u32 s68, 120
	s_cbranch_scc0 .Lmy_ssq_skip
	s_add_u32 s46, s46, 0x20000
	s_addc_u32 s47, s47, 0
	s_xor_b32 m0, m0, 0x4000
	s_nop 0
	global_load_lds_dwordx4 v128, s[46:47]
	global_load_lds_dwordx4 v128, s[46:47] offset:1024

.LBB0_67:
	s_lshl_b32 s33, s68, 8
	s_add_i32 s33, s33, s79
	v_or_b32_e32 v168, s33, v184
	v_lshl_or_b32 v166, s26, 8, v186
	s_mov_b64 s[40:41], -1
	s_and_b64 vcc, exec, s[64:65]
	s_cbranch_vccz .LBB0_101
	s_lshl_b32 s42, s68, 11
	s_and_b32 s42, s42, 0x4000
	s_lshl_b32 s43, s79, 6
	s_add_i32 s42, s42, s43
	s_add_i32 s42, s42, 0x20000
	v_lshl_add_u32 v128, v187, 6, s42
	ds_read_b128 v[132:135], v128 offset:0
	ds_read_b128 v[136:139], v128 offset:16
	ds_read_b128 v[140:143], v128 offset:32
	ds_read_b128 v[144:147], v128 offset:48
	ds_read_b128 v[148:151], v128 offset:8192
	ds_read_b128 v[152:155], v128 offset:8208
	ds_read_b128 v[170:173], v128 offset:8224
	ds_read_b128 v[174:177], v128 offset:8240
	v_mul_u32_u24_e32 v129, s32, v184
	v_and_b32_e32 v130, 24, v186
	v_add_lshl_u32 v129, v129, v130, 1
	s_mul_i32 s42, s33, s32
	s_lshl_b32 s43, s26, 8
	s_add_i32 s42, s42, s43
	s_lshl_b32 s43, s77, 5
	s_add_i32 s42, s42, s43
	s_lshl_b32 s42, s42, 1
	s_add_u32 s42, s16, s42
	s_addc_u32 s43, s17, 0
	s_lshl_b32 s46, s32, 5
	s_lshl_b32 s47, s32, 7
	v_lshlrev_b32_e32 v131, 2, v184
	s_waitcnt lgkmcnt(4)
	v_add_f32_e32 v132, v132, v133
	v_add_f32_e32 v134, v134, v135
	v_add_f32_e32 v132, v132, v134
	v_add_f32_e32 v136, v136, v137
	v_add_f32_e32 v138, v138, v139
	v_add_f32_e32 v136, v136, v138
	v_add_f32_e32 v140, v140, v141
	v_add_f32_e32 v142, v142, v143
	v_add_f32_e32 v140, v140, v142
	v_add_f32_e32 v144, v144, v145
	v_add_f32_e32 v146, v146, v147
	v_add_f32_e32 v144, v144, v146
	v_add_f32_e32 v132, v132, v136
	v_add_f32_e32 v140, v140, v144
	v_add_f32_e32 v132, v132, v140
	v_fmamk_f32 v132, v132, 0x3a800000, v194
	v_rsq_f32_e32 v178, v132
	s_waitcnt lgkmcnt(0)
	v_add_f32_e32 v148, v148, v149
	v_add_f32_e32 v150, v150, v151
	v_add_f32_e32 v148, v148, v150
	v_add_f32_e32 v152, v152, v153
	v_add_f32_e32 v154, v154, v155
	v_add_f32_e32 v152, v152, v154
	v_add_f32_e32 v170, v170, v171
	v_add_f32_e32 v172, v172, v173
	v_add_f32_e32 v170, v170, v172
	v_add_f32_e32 v174, v174, v175
	v_add_f32_e32 v176, v176, v177
	v_add_f32_e32 v174, v174, v176
	v_add_f32_e32 v148, v148, v152
	v_add_f32_e32 v170, v170, v174
	v_add_f32_e32 v148, v148, v170
	v_fmamk_f32 v148, v148, 0x3a800000, v194
	v_rsq_f32_e32 v180, v148
	s_nop 1
	ds_bpermute_b32 v214, v131, v178
	ds_bpermute_b32 v216, v131, v178 offset:64
	ds_bpermute_b32 v218, v131, v178 offset:128
	ds_bpermute_b32 v220, v131, v178 offset:192
	ds_bpermute_b32 v222, v131, v180
	ds_bpermute_b32 v224, v131, v180 offset:64
	ds_bpermute_b32 v226, v131, v180 offset:128
	ds_bpermute_b32 v228, v131, v180 offset:192
	s_and_b64 vcc, exec, s[8:9]
	s_cbranch_vccnz .Lmy_epi_m1
	s_waitcnt lgkmcnt(7)
	v_pk_mul_f32 v[132:133], v[124:125], v[214:215] op_sel_hi:[1,0]
	v_pk_mul_f32 v[134:135], v[126:127], v[214:215] op_sel_hi:[1,0]
	v_pk_mul_f32 v[136:137], v[120:121], v[214:215] op_sel_hi:[1,0]
	v_pk_mul_f32 v[138:139], v[122:123], v[214:215] op_sel_hi:[1,0]
	v_cvt_pk_bf16_f32 v140, v132, v133
	v_cvt_pk_bf16_f32 v141, v134, v135
	v_cvt_pk_bf16_f32 v142, v136, v137
	v_cvt_pk_bf16_f32 v143, v138, v139
	global_store_dwordx4 v129, v[140:143], s[42:43]
	v_pk_mul_f32 v[144:145], v[116:117], v[214:215] op_sel_hi:[1,0]
	v_pk_mul_f32 v[146:147], v[118:119], v[214:215] op_sel_hi:[1,0]
	v_pk_mul_f32 v[148:149], v[112:113], v[214:215] op_sel_hi:[1,0]
	v_pk_mul_f32 v[150:151], v[114:115], v[214:215] op_sel_hi:[1,0]
	v_cvt_pk_bf16_f32 v152, v144, v145
	v_cvt_pk_bf16_f32 v153, v146, v147
	v_cvt_pk_bf16_f32 v154, v148, v149
	v_cvt_pk_bf16_f32 v155, v150, v151
	global_store_dwordx4 v129, v[152:155], s[42:43] offset:256
	s_add_u32 s42, s42, s46
	s_addc_u32 s43, s43, 0
	s_waitcnt lgkmcnt(6)
	v_pk_mul_f32 v[132:133], v[108:109], v[216:217] op_sel_hi:[1,0]
	v_pk_mul_f32 v[134:135], v[110:111], v[216:217] op_sel_hi:[1,0]
	v_pk_mul_f32 v[136:137], v[104:105], v[216:217] op_sel_hi:[1,0]
	v_pk_mul_f32 v[138:139], v[106:107], v[216:217] op_sel_hi:[1,0]
	v_cvt_pk_bf16_f32 v140, v132, v133
	v_cvt_pk_bf16_f32 v141, v134, v135
	v_cvt_pk_bf16_f32 v142, v136, v137
	v_cvt_pk_bf16_f32 v143, v138, v139
	global_store_dwordx4 v129, v[140:143], s[42:43]
	v_pk_mul_f32 v[144:145], v[100:101], v[216:217] op_sel_hi:[1,0]
	v_pk_mul_f32 v[146:147], v[102:103], v[216:217] op_sel_hi:[1,0]
	v_pk_mul_f32 v[148:149], v[96:97], v[216:217] op_sel_hi:[1,0]
	v_pk_mul_f32 v[150:151], v[98:99], v[216:217] op_sel_hi:[1,0]
	v_cvt_pk_bf16_f32 v152, v144, v145
	v_cvt_pk_bf16_f32 v153, v146, v147
	v_cvt_pk_bf16_f32 v154, v148, v149
	v_cvt_pk_bf16_f32 v155, v150, v151
	global_store_dwordx4 v129, v[152:155], s[42:43] offset:256
	s_add_u32 s42, s42, s46
	s_addc_u32 s43, s43, 0
	s_waitcnt lgkmcnt(5)
	v_pk_mul_f32 v[132:133], v[92:93], v[218:219] op_sel_hi:[1,0]
	v_pk_mul_f32 v[134:135], v[94:95], v[218:219] op_sel_hi:[1,0]
	v_pk_mul_f32 v[136:137], v[88:89], v[218:219] op_sel_hi:[1,0]
	v_pk_mul_f32 v[138:139], v[90:91], v[218:219] op_sel_hi:[1,0]
	v_cvt_pk_bf16_f32 v140, v132, v133
	v_cvt_pk_bf16_f32 v141, v134, v135
	v_cvt_pk_bf16_f32 v142, v136, v137
	v_cvt_pk_bf16_f32 v143, v138, v139
	global_store_dwordx4 v129, v[140:143], s[42:43]
	v_pk_mul_f32 v[144:145], v[84:85], v[218:219] op_sel_hi:[1,0]
	v_pk_mul_f32 v[146:147], v[86:87], v[218:219] op_sel_hi:[1,0]
	v_pk_mul_f32 v[148:149], v[80:81], v[218:219] op_sel_hi:[1,0]
	v_pk_mul_f32 v[150:151], v[82:83], v[218:219] op_sel_hi:[1,0]
	v_cvt_pk_bf16_f32 v152, v144, v145
	v_cvt_pk_bf16_f32 v153, v146, v147
	v_cvt_pk_bf16_f32 v154, v148, v149
	v_cvt_pk_bf16_f32 v155, v150, v151
	global_store_dwordx4 v129, v[152:155], s[42:43] offset:256
	s_add_u32 s42, s42, s46
	s_addc_u32 s43, s43, 0
	s_waitcnt lgkmcnt(4)
	v_pk_mul_f32 v[132:133], v[76:77], v[220:221] op_sel_hi:[1,0]
	v_pk_mul_f32 v[134:135], v[78:79], v[220:221] op_sel_hi:[1,0]
	v_pk_mul_f32 v[136:137], v[72:73], v[220:221] op_sel_hi:[1,0]
	v_pk_mul_f32 v[138:139], v[74:75], v[220:221] op_sel_hi:[1,0]
	v_cvt_pk_bf16_f32 v140, v132, v133
	v_cvt_pk_bf16_f32 v141, v134, v135
	v_cvt_pk_bf16_f32 v142, v136, v137
	v_cvt_pk_bf16_f32 v143, v138, v139
	global_store_dwordx4 v129, v[140:143], s[42:43]
	v_pk_mul_f32 v[144:145], v[68:69], v[220:221] op_sel_hi:[1,0]
	v_pk_mul_f32 v[146:147], v[70:71], v[220:221] op_sel_hi:[1,0]
	v_pk_mul_f32 v[148:149], v[64:65], v[220:221] op_sel_hi:[1,0]
	v_pk_mul_f32 v[150:151], v[66:67], v[220:221] op_sel_hi:[1,0]
	v_cvt_pk_bf16_f32 v152, v144, v145
	v_cvt_pk_bf16_f32 v153, v146, v147
	v_cvt_pk_bf16_f32 v154, v148, v149
	v_cvt_pk_bf16_f32 v155, v150, v151
	global_store_dwordx4 v129, v[152:155], s[42:43] offset:256
	s_add_u32 s42, s42, s46
	s_addc_u32 s43, s43, 0
	s_add_u32 s42, s42, s47
	s_addc_u32 s43, s43, 0
	s_waitcnt lgkmcnt(3)
	v_pk_mul_f32 v[132:133], v[60:61], v[222:223] op_sel_hi:[1,0]
	v_pk_mul_f32 v[134:135], v[62:63], v[222:223] op_sel_hi:[1,0]
	v_pk_mul_f32 v[136:137], v[56:57], v[222:223] op_sel_hi:[1,0]
	v_pk_mul_f32 v[138:139], v[58:59], v[222:223] op_sel_hi:[1,0]
	v_cvt_pk_bf16_f32 v140, v132, v133
	v_cvt_pk_bf16_f32 v141, v134, v135
	v_cvt_pk_bf16_f32 v142, v136, v137
	v_cvt_pk_bf16_f32 v143, v138, v139
	global_store_dwordx4 v129, v[140:143], s[42:43]
	v_pk_mul_f32 v[144:145], v[52:53], v[222:223] op_sel_hi:[1,0]
	v_pk_mul_f32 v[146:147], v[54:55], v[222:223] op_sel_hi:[1,0]
	v_pk_mul_f32 v[148:149], v[48:49], v[222:223] op_sel_hi:[1,0]
	v_pk_mul_f32 v[150:151], v[50:51], v[222:223] op_sel_hi:[1,0]
	v_cvt_pk_bf16_f32 v152, v144, v145
	v_cvt_pk_bf16_f32 v153, v146, v147
	v_cvt_pk_bf16_f32 v154, v148, v149
	v_cvt_pk_bf16_f32 v155, v150, v151
	global_store_dwordx4 v129, v[152:155], s[42:43] offset:256
	s_add_u32 s42, s42, s46
	s_addc_u32 s43, s43, 0
	s_waitcnt lgkmcnt(2)
	v_pk_mul_f32 v[132:133], v[44:45], v[224:225] op_sel_hi:[1,0]
	v_pk_mul_f32 v[134:135], v[46:47], v[224:225] op_sel_hi:[1,0]
	v_pk_mul_f32 v[136:137], v[40:41], v[224:225] op_sel_hi:[1,0]
	v_pk_mul_f32 v[138:139], v[42:43], v[224:225] op_sel_hi:[1,0]
	v_cvt_pk_bf16_f32 v140, v132, v133
	v_cvt_pk_bf16_f32 v141, v134, v135
	v_cvt_pk_bf16_f32 v142, v136, v137
	v_cvt_pk_bf16_f32 v143, v138, v139
	global_store_dwordx4 v129, v[140:143], s[42:43]
	v_pk_mul_f32 v[144:145], v[36:37], v[224:225] op_sel_hi:[1,0]
	v_pk_mul_f32 v[146:147], v[38:39], v[224:225] op_sel_hi:[1,0]
	v_pk_mul_f32 v[148:149], v[32:33], v[224:225] op_sel_hi:[1,0]
	v_pk_mul_f32 v[150:151], v[34:35], v[224:225] op_sel_hi:[1,0]
	v_cvt_pk_bf16_f32 v152, v144, v145
	v_cvt_pk_bf16_f32 v153, v146, v147
	v_cvt_pk_bf16_f32 v154, v148, v149
	v_cvt_pk_bf16_f32 v155, v150, v151
	global_store_dwordx4 v129, v[152:155], s[42:43] offset:256
	s_add_u32 s42, s42, s46
	s_addc_u32 s43, s43, 0
	s_waitcnt lgkmcnt(1)
	v_pk_mul_f32 v[132:133], v[28:29], v[226:227] op_sel_hi:[1,0]
	v_pk_mul_f32 v[134:135], v[30:31], v[226:227] op_sel_hi:[1,0]
	v_pk_mul_f32 v[136:137], v[24:25], v[226:227] op_sel_hi:[1,0]
	v_pk_mul_f32 v[138:139], v[26:27], v[226:227] op_sel_hi:[1,0]
	v_cvt_pk_bf16_f32 v140, v132, v133
	v_cvt_pk_bf16_f32 v141, v134, v135
	v_cvt_pk_bf16_f32 v142, v136, v137
	v_cvt_pk_bf16_f32 v143, v138, v139
	global_store_dwordx4 v129, v[140:143], s[42:43]
	v_pk_mul_f32 v[144:145], v[20:21], v[226:227] op_sel_hi:[1,0]
	v_pk_mul_f32 v[146:147], v[22:23], v[226:227] op_sel_hi:[1,0]
	v_pk_mul_f32 v[148:149], v[16:17], v[226:227] op_sel_hi:[1,0]
	v_pk_mul_f32 v[150:151], v[18:19], v[226:227] op_sel_hi:[1,0]
	v_cvt_pk_bf16_f32 v152, v144, v145
	v_cvt_pk_bf16_f32 v153, v146, v147
	v_cvt_pk_bf16_f32 v154, v148, v149
	v_cvt_pk_bf16_f32 v155, v150, v151
	global_store_dwordx4 v129, v[152:155], s[42:43] offset:256
	s_add_u32 s42, s42, s46
	s_addc_u32 s43, s43, 0
	s_waitcnt lgkmcnt(0)
	v_pk_mul_f32 v[132:133], v[12:13], v[228:229] op_sel_hi:[1,0]
	v_pk_mul_f32 v[134:135], v[14:15], v[228:229] op_sel_hi:[1,0]
	v_pk_mul_f32 v[136:137], v[8:9], v[228:229] op_sel_hi:[1,0]
	v_pk_mul_f32 v[138:139], v[10:11], v[228:229] op_sel_hi:[1,0]
	v_cvt_pk_bf16_f32 v140, v132, v133
	v_cvt_pk_bf16_f32 v141, v134, v135
	v_cvt_pk_bf16_f32 v142, v136, v137
	v_cvt_pk_bf16_f32 v143, v138, v139
	global_store_dwordx4 v129, v[140:143], s[42:43]
	v_pk_mul_f32 v[144:145], v[4:5], v[228:229] op_sel_hi:[1,0]
	v_pk_mul_f32 v[146:147], v[6:7], v[228:229] op_sel_hi:[1,0]
	v_pk_mul_f32 v[148:149], v[0:1], v[228:229] op_sel_hi:[1,0]
	v_pk_mul_f32 v[150:151], v[2:3], v[228:229] op_sel_hi:[1,0]
	v_cvt_pk_bf16_f32 v152, v144, v145
	v_cvt_pk_bf16_f32 v153, v146, v147
	v_cvt_pk_bf16_f32 v154, v148, v149
	v_cvt_pk_bf16_f32 v155, v150, v151
	global_store_dwordx4 v129, v[152:155], s[42:43] offset:256
	s_mov_b64 s[40:41], 0
	s_branch .LBB0_101
